# GQA loop: softmax reference folded into the QK MFMA accumulator init for both query sub-blocks (64 fewer VALU subs per tile); the 32 registers holding -ref are parked in per-thread LDS slots meanwhile
# speedup vs baseline: 1.3193x; 1.0090x over previous
; #define DECODE2(it) int b, hd; size_t q0; int nT; \
;     if ((it) < NL2) { b = (it) >> 6; hd = ((it) >> 4) & 3; q0 = (size_t)b * SEQA + CTXL + ((it) & 15) * 256; nT = 68; } \
;     else { int j_ = (it) - NL2; b = j_ >> 2; hd = j_ & 3; q0 = (size_t)b * SEQA; nT = 4; }
; template <int DK>
; DI void attn_item2(const u16* __restrict__ Q, int ldq, const u16* __restrict__ K, int ldk, const u16* __restrict__ Vt, int nTiles,
;                    u16* __restrict__ Gp, const u16* __restrict__ Zp, char* smem, int tid) {
;     ...
;   const int lane = tid & 63, w = tid >> 6, r = lane & 31, h = lane >> 5;
;   __syncthreads();
;   bf16x8 qf[2][KS];
; #pragma unroll
;   for (int qw = 0; qw < 2; qw++) {
;     const u16* qrow = Q + (size_t)((w * 2 + qw) * 32 + r) * ldq + h * 8;
; #pragma unroll
;     for (int ks = 0; ks < KS; ks++) qf[qw][ks] = *(const bf16x8*)(qrow + ks * 16);
;   }
;   f32x16 o[2][2];
; #pragma unroll
;   for (int i = 0; i < 16; i++) { o[0][0][i] = 0.f; o[0][1][i] = 0.f; o[1][0][i] = 0.f; o[1][1][i] = 0.f; }
;   float m_run0 = -1e30f, m_run1 = -1e30f, l_run0 = 0.f, l_run1 = 0.f;
;   uint4 rk0, rk1, rk2, rv0, rv1;
;   rk2 = make_uint4(0, 0, 0, 0);
;   const int kr0 = tid / KCH, kc0 = (tid % KCH) * 8, kr1 = (tid + 256) / KCH, kc1 = ((tid + 256) % KCH) * 8, kr2 = (tid + 512) / KCH, kc2 = ((tid + 512) % KCH) * 8;
;   const int vd0 = tid >> 3, vk0 = (tid & 7) * 8;
; DI void phase_mix(const Params& p, int l, char* smem, int tid) {
;     ...
;   for (int it = fetch_item(q, smem); it < NT2; it = fetch_item(q, smem)) {
;     DECODE2(it)
;     const int hk = hd >> 1;
;     attn_item2<64>(p.QD + q0 * 256 + hd * 64, 256, p.KD + ((size_t)b * 2 + hk) * SEQA * 64, 64, p.VtAD + ((size_t)b * 384 + 256 + hk * 64) * SEQA, nT,
;                    p.G + q0 * 1024 + 768 + hd * 64, p.Pk + q0 * PKW + 768 + 768 + hd * 64, smem, tid);
.LBB0_852:
	s_or_b64 exec, exec, s[0:1]
	s_waitcnt lgkmcnt(0)
	s_barrier
	flat_load_dword v2, v[154:155] sc0 sc1
	s_waitcnt vmcnt(0)
	v_readlane_b32 s0, v254, 17
	v_readlane_b32 s1, v254, 18
	s_and_b64 s[0:1], s[0:1], exec
	s_movk_i32 s0, 0x220
	s_cselect_b32 s10, s0, 0x200
	s_waitcnt lgkmcnt(0)
	v_cmp_gt_i32_e32 vcc, s10, v2
	s_and_saveexec_b64 s[0:1], vcc
	s_cbranch_execz .LBB0_881
	v_ashrrev_i32_e32 v8, 31, v156
	v_lshrrev_b32_e32 v8, 29, v8
	v_add_u32_e32 v9, v156, v8
	v_ashrrev_i32_e32 v8, 3, v9
	v_and_b32_e32 v9, -8, v9
	v_sub_u32_e32 v14, v156, v9
	v_add_u32_e32 v9, 0x100, v156
	v_ashrrev_i32_e32 v10, 31, v9
	v_lshrrev_b32_e32 v10, 29, v10
	v_add_u32_e32 v11, v9, v10
	v_ashrrev_i32_e32 v10, 3, v11
	v_and_b32_e32 v11, -8, v11
	v_sub_u32_e32 v15, v9, v11
	v_lshlrev_b32_e32 v9, 3, v156
	v_ashrrev_i32_e32 v16, 3, v156
	v_and_b32_e32 v12, 56, v9
	v_ashrrev_i32_e32 v9, 31, v8
	v_lshlrev_b64 v[166:167], 7, v[8:9]
	v_add_u32_e32 v9, 32, v16
	v_bfe_u32 v3, v156, 5, 1
	v_mad_i64_i32 v[170:171], s[2:3], v16, s23, 0
	v_mad_i64_i32 v[172:173], s[2:3], v9, s23, 0
	v_and_b32_e32 v13, 31, v156
	s_movk_i32 s3, 0x90
	v_lshlrev_b32_e32 v9, 4, v3
	v_mul_lo_u32 v149, v8, s3
	v_mul_u32_u24_e32 v8, 0x90, v13
	v_mad_u32_u24 v225, v13, s3, v9
	v_lshlrev_b32_e32 v9, 3, v13
	v_and_b32_e32 v4, 0xffffffdf, v156
	v_lshlrev_b32_e32 v0, 3, v3
	v_or_b32_e32 v6, 32, v156
	s_movk_i32 s2, 0x88
	v_sub_u32_e32 v8, v8, v9
	v_ashrrev_i32_e32 v5, 31, v4
	v_lshlrev_b32_e32 v162, 3, v14
	v_mul_lo_u32 v153, v10, s3
	v_mul_lo_u32 v197, v16, s2
	v_add_u32_e32 v226, v8, v0
	v_lshlrev_b32_e32 v8, 2, v3
	v_mad_i64_i32 v[174:175], s[2:3], v4, s33, 0
	v_mad_i64_i32 v[178:179], s[2:3], v6, s33, 0
	v_and_b32_e32 v3, 7, v156
	v_lshlrev_b64 v[158:159], 9, v[4:5]
	v_lshlrev_b32_e32 v164, 3, v15
	v_ashrrev_i32_e32 v163, 31, v162
	v_ashrrev_i32_e32 v11, 31, v10
	v_lshlrev_b64 v[176:177], 11, v[4:5]
	v_lshl_or_b32 v4, v3, 4, v170
	v_mov_b32_e32 v5, v171
	v_readlane_b32 s2, v254, 5
	v_lshlrev_b64 v[168:169], 7, v[10:11]
	v_ashrrev_i32_e32 v165, 31, v164
	v_lshl_add_u64 v[182:183], s[96:97], 0, v[4:5]
	v_lshl_add_u64 v[4:5], v[162:163], 1, v[166:167]
	v_readlane_b32 s3, v254, 6
	v_ashrrev_i32_e32 v7, 31, v6
	v_lshlrev_b64 v[160:161], 9, v[6:7]
	v_lshl_add_u64 v[184:185], s[2:3], 0, v[4:5]
	v_lshl_add_u64 v[4:5], v[164:165], 1, v[168:169]
	v_lshl_add_u32 v151, v14, 4, v149
	v_lshl_add_u32 v157, v15, 4, v153
	v_lshl_add_u32 v224, v12, 1, v197
	v_lshlrev_b64 v[180:181], 11, v[6:7]
	v_lshl_add_u64 v[186:187], s[2:3], 0, v[4:5]
	s_mov_b64 s[4:5], 0
	v_lshlrev_b32_e32 v188, 1, v0
	v_lshlrev_b32_e32 v227, 1, v162
	v_lshlrev_b32_e32 v228, 1, v164
	v_lshlrev_b32_e32 v190, 1, v12
	v_lshlrev_b32_e32 v192, 1, v8
	v_lshlrev_b32_e32 v14, 2, v206
	ds_write_b32 v14, v208 offset:36864
	ds_write_b32 v14, v209 offset:37888
	ds_write_b32 v14, v210 offset:38912
	ds_write_b32 v14, v211 offset:39936
	ds_write_b32 v14, v212 offset:40960
	ds_write_b32 v14, v213 offset:41984
	ds_write_b32 v14, v214 offset:43008
	ds_write_b32 v14, v215 offset:44032
	ds_write_b32 v14, v216 offset:45056
	ds_write_b32 v14, v217 offset:46080
	ds_write_b32 v14, v218 offset:47104
	ds_write_b32 v14, v219 offset:48128
	ds_write_b32 v14, v220 offset:49152
	ds_write_b32 v14, v221 offset:50176
	ds_write_b32 v14, v222 offset:51200
	ds_write_b32 v14, v223 offset:52224
	s_waitcnt lgkmcnt(0)
	s_branch .LBB0_856

; #define GLOAD(t) { const int pos0_ = TILE_POS(t); \
;     rk0 = *(const uint4*)(K + (size_t)(pos0_ + kr0) * ldk + kc0); rk1 = *(const uint4*)(K + (size_t)(pos0_ + kr1) * ldk + kc1); \
;     if (NKC == 3) rk2 = *(const uint4*)(K + (size_t)(pos0_ + kr2) * ldk + kc2); \
;     rv0 = *(const uint4*)(Vt + (size_t)vd0 * SEQA + pos0_ + vk0); rv1 = *(const uint4*)(Vt + (size_t)(vd0 + 32) * SEQA + pos0_ + vk0); }
; #define LSTORE(bf) { *(uint4*)&Ks[bf][kr0][kc0] = rk0; *(uint4*)&Ks[bf][kr1][kc1] = rk1; if (NKC == 3) *(uint4*)&Ks[bf][kr2][kc2] = rk2; \
;     *(uint2*)&Vs[bf][vd0][vk0] = make_uint2(rv0.x, rv0.y); *(uint2*)&Vs[bf][vd0][vk0 + 4] = make_uint2(rv0.z, rv0.w); \
;     *(uint2*)&Vs[bf][vd0 + 32][vk0] = make_uint2(rv1.x, rv1.y); *(uint2*)&Vs[bf][vd0 + 32][vk0 + 4] = make_uint2(rv1.z, rv1.w); }
; #define GLOAD(t) { const int pos0_ = (t) * 64; \
;     rk0 = *(const uint4*)(K + (size_t)(pos0_ + kr0) * ldk + kc0); rk1 = *(const uint4*)(K + (size_t)(pos0_ + kr1) * ldk + kc1); \
;     if (NKC == 3) rk2 = *(const uint4*)(K + (size_t)(pos0_ + kr2) * ldk + kc2); \
;     rv0 = *(const uint4*)(Vt + (size_t)vd0 * SEQA + pos0_ + vk0); rv1 = *(const uint4*)(Vt + (size_t)(vd0 + 32) * SEQA + pos0_ + vk0); }
; template <int DK>
; DI void attn_item2(const u16* __restrict__ Q, int ldq, const u16* __restrict__ K, int ldk, const u16* __restrict__ Vt, int nTiles,
;                    u16* __restrict__ Gp, const u16* __restrict__ Zp, char* smem, int tid) {
;     ...
;   __syncthreads();
;   bf16x8 qf[2][KS];
; #pragma unroll
;   for (int qw = 0; qw < 2; qw++) {
;     const u16* qrow = Q + (size_t)((w * 2 + qw) * 32 + r) * ldq + h * 8;
; #pragma unroll
;     for (int ks = 0; ks < KS; ks++) qf[qw][ks] = *(const bf16x8*)(qrow + ks * 16);
;   }
;   f32x16 o[2][2];
; #pragma unroll
;   for (int i = 0; i < 16; i++) { o[0][0][i] = 0.f; o[0][1][i] = 0.f; o[1][0][i] = 0.f; o[1][1][i] = 0.f; }
;   float m_run0 = -1e30f, m_run1 = -1e30f, l_run0 = 0.f, l_run1 = 0.f;
;   uint4 rk0, rk1, rk2, rv0, rv1;
;   rk2 = make_uint4(0, 0, 0, 0);
;   const int kr0 = tid / KCH, kc0 = (tid % KCH) * 8, kr1 = (tid + 256) / KCH, kc1 = ((tid + 256) % KCH) * 8, kr2 = (tid + 512) / KCH, kc2 = ((tid + 512) % KCH) * 8;
;   const int vd0 = tid >> 3, vk0 = (tid & 7) * 8;
;     ...
;   GLOAD(0); LSTORE(0);
;   __syncthreads();
.LBB0_860:
	s_or_b64 exec, exec, s[6:7]
	v_readlane_b32 s2, v253, 42
	v_bfe_u32 v26, v2, 1, 1
	v_lshlrev_b64 v[4:5], 1, v[8:9]
	v_readlane_b32 s3, v253, 43
	v_or_b32_e32 v0, v4, v26
	s_movk_i32 s6, 0x180
	v_mov_b64_e32 v[6:7], s[2:3]
	v_mad_u64_u32 v[6:7], s[2:3], v0, s14, v[6:7]
	v_mov_b32_e32 v0, v7
	v_mad_u64_u32 v[4:5], s[2:3], v5, s14, v[0:1]
	v_mov_b32_e32 v7, v4
	v_mad_u64_u32 v[4:5], s[2:3], v8, s6, 0
	v_mov_b32_e32 v0, v5
	v_mad_u64_u32 v[10:11], s[2:3], v9, s6, v[0:1]
	v_lshl_or_b32 v4, v26, 6, v4
	v_mov_b32_e32 v5, v10
	s_mov_b64 s[2:3], 0x100
	v_lshl_add_u64 v[4:5], v[4:5], 0, s[2:3]
	v_mov_b64_e32 v[10:11], s[42:43]
	v_mad_u64_u32 v[18:19], s[2:3], v4, s23, v[10:11]
	v_mov_b32_e32 v0, v19
	v_mad_u64_u32 v[4:5], s[2:3], v5, s23, v[0:1]
	v_mov_b32_e32 v19, v4
	v_lshl_add_u64 v[4:5], v[6:7], 0, v[166:167]
	v_lshl_add_u64 v[4:5], v[162:163], 1, v[4:5]
	v_lshl_add_u64 v[6:7], v[6:7], 0, v[168:169]
	s_barrier
	v_lshl_add_u64 v[6:7], v[164:165], 1, v[6:7]
	global_load_dwordx4 v[10:13], v[4:5], off
	global_load_dwordx4 v[14:17], v[6:7], off
	v_lshl_add_u64 v[4:5], v[18:19], 0, v[170:171]
	v_mov_b32_e32 v191, v1
	v_lshl_add_u64 v[4:5], v[4:5], 0, v[190:191]
	v_lshl_add_u64 v[6:7], v[18:19], 0, v[172:173]
	v_lshl_add_u64 v[6:7], v[6:7], 0, v[190:191]
	global_load_dwordx4 v[18:21], v[4:5], off
	global_load_dwordx4 v[22:25], v[6:7], off
	v_and_b32_e32 v27, 3, v2
	v_lshlrev_b64 v[4:5], 9, v[194:195]
	v_lshl_add_u64 v[4:5], s[40:41], 0, v[4:5]
	v_lshlrev_b32_e32 v0, 7, v27
	v_lshl_add_u64 v[4:5], v[4:5], 0, v[0:1]
	v_mov_b32_e32 v189, v1
	v_lshl_add_u64 v[4:5], v[4:5], 0, v[188:189]
	v_lshl_add_u64 v[6:7], v[4:5], 0, v[158:159]
	v_lshl_add_u64 v[4:5], v[4:5], 0, v[160:161]
	global_load_dwordx4 v[132:135], v[6:7], off
	global_load_dwordx4 v[124:127], v[6:7], off offset:32
	global_load_dwordx4 v[120:123], v[6:7], off offset:64
	global_load_dwordx4 v[112:115], v[6:7], off offset:96
	global_load_dwordx4 v[140:143], v[4:5], off
	global_load_dwordx4 v[136:139], v[4:5], off offset:32
	global_load_dwordx4 v[128:131], v[4:5], off offset:64
	global_load_dwordx4 v[116:119], v[4:5], off offset:96
	v_mad_u64_u32 v[198:199], s[2:3], v8, s15, v[182:183]
	v_mov_b32_e32 v0, v199
	v_add_u32_e32 v28, 0x4800, v224
	v_add_u32_e32 v29, 0x5900, v224
	v_mad_u64_u32 v[200:201], s[2:3], v8, s11, v[184:185]
	v_mul_lo_u32 v30, v9, s11
	v_mad_u64_u32 v[202:203], s[2:3], v8, s11, v[186:187]
	v_mad_u64_u32 v[8:9], s[6:7], v9, s15, v[0:1]
	v_add_u32_e32 v193, 1, v3
	v_mov_b32_e32 v2, v1
	v_mov_b32_e32 v3, v1
	v_mov_b32_e32 v4, v1
	v_mov_b32_e32 v5, v1
	v_mov_b32_e32 v6, v1
	v_mov_b32_e32 v7, v1
	v_lshlrev_b32_e32 v196, 6, v27
	v_mul_hi_u32_u24_e32 v205, 0x88000, v26
	v_mul_u32_u24_e32 v204, 0x88000, v26
	v_add_u32_e32 v201, v30, v201
	v_add_u32_e32 v203, v30, v203
	v_mov_b32_e32 v0, v1
	v_mov_b32_e32 v199, v8
	v_mov_b32_e32 v8, v1
	v_mov_b32_e32 v9, v1
	s_mov_b32 s2, 0
	v_mov_b32_e32 v229, 0
	v_mov_b32_e32 v191, 0xf149f2ca
	s_mov_b64 s[6:7], 0
	v_mov_b32_e32 v189, 0xf149f2ca
	s_waitcnt vmcnt(11)
	ds_write_b128 v151, v[10:13]
	s_waitcnt vmcnt(10)
	ds_write_b128 v157, v[14:17]
	s_waitcnt vmcnt(9)
	ds_write2_b64 v28, v[18:19], v[20:21] offset1:1
	s_waitcnt vmcnt(8)
	ds_write2_b64 v29, v[22:23], v[24:25] offset1:1
	v_mov_b32_e32 v14, v1
	v_mov_b32_e32 v15, v1
	v_mov_b32_e32 v10, v1
	v_mov_b32_e32 v11, v1
	v_mov_b32_e32 v12, v1
	v_mov_b32_e32 v13, v1
	v_mov_b64_e32 v[30:31], v[14:15]
	v_mov_b64_e32 v[46:47], v[14:15]
	v_mov_b64_e32 v[62:63], v[14:15]
	v_mov_b64_e32 v[78:79], v[14:15]
	v_mov_b64_e32 v[28:29], v[12:13]
	v_mov_b64_e32 v[26:27], v[10:11]
	v_mov_b64_e32 v[24:25], v[8:9]
	v_mov_b64_e32 v[22:23], v[6:7]
	v_mov_b64_e32 v[20:21], v[4:5]
	v_mov_b64_e32 v[18:19], v[2:3]
	v_mov_b64_e32 v[16:17], v[0:1]
	v_mov_b64_e32 v[44:45], v[12:13]
	v_mov_b64_e32 v[42:43], v[10:11]
	v_mov_b64_e32 v[40:41], v[8:9]
	v_mov_b64_e32 v[38:39], v[6:7]
	v_mov_b64_e32 v[36:37], v[4:5]
	v_mov_b64_e32 v[34:35], v[2:3]
	v_mov_b64_e32 v[32:33], v[0:1]
	v_mov_b64_e32 v[60:61], v[12:13]
	v_mov_b64_e32 v[58:59], v[10:11]
	v_mov_b64_e32 v[56:57], v[8:9]
	v_mov_b64_e32 v[54:55], v[6:7]
	v_mov_b64_e32 v[52:53], v[4:5]
	v_mov_b64_e32 v[50:51], v[2:3]
	v_mov_b64_e32 v[48:49], v[0:1]
	v_mov_b64_e32 v[76:77], v[12:13]
	v_mov_b64_e32 v[74:75], v[10:11]
	v_mov_b64_e32 v[72:73], v[8:9]
	v_mov_b64_e32 v[70:71], v[6:7]
	v_mov_b64_e32 v[68:69], v[4:5]
	v_mov_b64_e32 v[66:67], v[2:3]
	v_mov_b64_e32 v[64:65], v[0:1]
	v_mov_b32_e32 v0, 0
	s_waitcnt lgkmcnt(0)
	s_barrier
	v_mov_b32_e32 v208, 0
	v_mov_b32_e32 v209, 0
	v_mov_b32_e32 v210, 0
	v_mov_b32_e32 v211, 0
	v_mov_b32_e32 v212, 0
	v_mov_b32_e32 v213, 0
	v_mov_b32_e32 v214, 0
	v_mov_b32_e32 v215, 0
	v_mov_b32_e32 v216, 0
	v_mov_b32_e32 v217, 0
	v_mov_b32_e32 v218, 0
	v_mov_b32_e32 v219, 0
	v_mov_b32_e32 v220, 0
	v_mov_b32_e32 v221, 0
	v_mov_b32_e32 v222, 0
	v_mov_b32_e32 v223, 0
	v_lshlrev_b32_e32 v14, 2, v206
	v_add_u32_e32 v14, 0xd000, v14
	ds_write_b32 v14, v160 offset:0
	ds_write_b32 v14, v161 offset:1024
	ds_write_b32 v14, v162 offset:2048
	ds_write_b32 v14, v163 offset:3072
	ds_write_b32 v14, v164 offset:4096
	ds_write_b32 v14, v165 offset:5120
	ds_write_b32 v14, v166 offset:6144
	ds_write_b32 v14, v167 offset:7168
	ds_write_b32 v14, v168 offset:8192
	ds_write_b32 v14, v169 offset:9216
	ds_write_b32 v14, v170 offset:10240
	ds_write_b32 v14, v171 offset:11264
	ds_write_b32 v14, v172 offset:12288
	ds_write_b32 v14, v173 offset:13312
	ds_write_b32 v14, v174 offset:14336
	ds_write_b32 v14, v175 offset:15360
	v_mov_b32_e32 v160, 0
	v_mov_b32_e32 v161, 0
	v_mov_b32_e32 v162, 0
	v_mov_b32_e32 v163, 0
	v_mov_b32_e32 v164, 0
	v_mov_b32_e32 v165, 0
	v_mov_b32_e32 v166, 0
	v_mov_b32_e32 v167, 0
	v_mov_b32_e32 v168, 0
	v_mov_b32_e32 v169, 0
	v_mov_b32_e32 v170, 0
	v_mov_b32_e32 v171, 0
	v_mov_b32_e32 v172, 0
	v_mov_b32_e32 v173, 0
	v_mov_b32_e32 v174, 0
	v_mov_b32_e32 v175, 0
	s_waitcnt lgkmcnt(0)
	s_branch .LBB0_862
; #define MFMA(a, b, c) __builtin_amdgcn_mfma_f32_32x32x16_bf16((a), (b), (c), 0, 0, 0)
; #define GLOAD(t) { const int pos0_ = TILE_POS(t); \
;     rk0 = *(const uint4*)(K + (size_t)(pos0_ + kr0) * ldk + kc0); rk1 = *(const uint4*)(K + (size_t)(pos0_ + kr1) * ldk + kc1); \
;     if (NKC == 3) rk2 = *(const uint4*)(K + (size_t)(pos0_ + kr2) * ldk + kc2); \
;     rv0 = *(const uint4*)(Vt + (size_t)vd0 * SEQA + pos0_ + vk0); rv1 = *(const uint4*)(Vt + (size_t)(vd0 + 32) * SEQA + pos0_ + vk0); }
; #define LSTORE(bf) { *(uint4*)&Ks[bf][kr0][kc0] = rk0; *(uint4*)&Ks[bf][kr1][kc1] = rk1; if (NKC == 3) *(uint4*)&Ks[bf][kr2][kc2] = rk2; \
;     *(uint2*)&Vs[bf][vd0][vk0] = make_uint2(rv0.x, rv0.y); *(uint2*)&Vs[bf][vd0][vk0 + 4] = make_uint2(rv0.z, rv0.w); \
;     *(uint2*)&Vs[bf][vd0 + 32][vk0] = make_uint2(rv1.x, rv1.y); *(uint2*)&Vs[bf][vd0 + 32][vk0 + 4] = make_uint2(rv1.z, rv1.w); }
; template <int DK>
; DI void attn_item2(const u16* __restrict__ Q, int ldq, const u16* __restrict__ K, int ldk, const u16* __restrict__ Vt, int nTiles,
;                    u16* __restrict__ Gp, const u16* __restrict__ Zp, char* smem, int tid) {
;     ...
;   for (int t = 0; t < nTiles; t++) {
;     const int buf = t & 1;
;     if (t + 1 < nTiles) GLOAD(t + 1);
; #pragma unroll
;     for (int kb = 0; kb < 2; kb++) {
;       f32x16 s0, s1;
; #pragma unroll
;       for (int i = 0; i < 16; i++) { s0[i] = 0.f; s1[i] = 0.f; }
; #pragma unroll
;       for (int ks = 0; ks < KS; ks++) {
;         bf16x8 a = *(const bf16x8*)&Ks[buf][kb * 32 + r][ks * 16 + h * 8];
;         s0 = MFMA(a, qf[0][ks], s0);
;         s1 = MFMA(a, qf[1][ks], s1);
;       }
;       bf16x8 pf0[2], pf1[2];
;     ...
;       SOFTMAX_STEP(s0, m_run0, l_run0, o[0], pf0)
;       SOFTMAX_STEP(s1, m_run1, l_run1, o[1], pf1)
;     ...
; #pragma unroll
;       for (int db = 0; db < 2; db++)
; #pragma unroll
;         for (int sx = 0; sx < 2; sx++) {
;           const u16* vp = &Vs[buf][db * 32 + r][32 * kb + 16 * sx + 4 * h];
;           uint2 lo = *(const uint2*)vp, hi = *(const uint2*)(vp + 8);
;           uint4 u; u.x = lo.x; u.y = lo.y; u.z = hi.x; u.w = hi.y;
;           const bf16x8 a = __builtin_bit_cast(bf16x8, u);
;           o[0][db] = MFMA(a, pf0[sx], o[0][db]);
;           o[1][db] = MFMA(a, pf1[sx], o[1][db]);
;         }
;     }
;     if (t + 1 < nTiles) LSTORE(buf ^ 1);
;     __syncthreads();
;   }
.LBB0_861:
	v_exp_f32_e32 v96, v96
	v_exp_f32_e32 v97, v97
	v_exp_f32_e32 v98, v98
	v_exp_f32_e32 v99, v99
	v_add_f32_e32 v230, 0, v96
	v_exp_f32_e32 v231, v100
	v_add_f32_e32 v230, v97, v230
	v_add_f32_e32 v230, v98, v230
	v_add_f32_e32 v230, v99, v230
	v_add_f32_e32 v100, v231, v230
	v_exp_f32_e32 v230, v101
	v_exp_f32_e32 v232, v102
	v_exp_f32_e32 v103, v103
	v_exp_f32_e32 v104, v104
	v_add_f32_e32 v100, v230, v100
	v_exp_f32_e32 v105, v105
	v_add_f32_e32 v100, v232, v100
	v_exp_f32_e32 v106, v106
	v_add_f32_e32 v100, v103, v100
	v_exp_f32_e32 v107, v107
	v_add_f32_e32 v100, v104, v100
	v_exp_f32_e32 v108, v108
	v_add_f32_e32 v100, v105, v100
	v_exp_f32_e32 v109, v109
	v_add_f32_e32 v100, v106, v100
	v_exp_f32_e32 v110, v110
	v_add_f32_e32 v100, v107, v100
	v_exp_f32_e32 v111, v111
	v_exp_f32_e32 v80, v80
	v_add_f32_e32 v100, v108, v100
	v_exp_f32_e32 v81, v81
	v_add_f32_e32 v100, v109, v100
	v_exp_f32_e32 v82, v82
	v_add_f32_e32 v100, v110, v100
	v_exp_f32_e32 v83, v83
	v_add_f32_e32 v233, v111, v100
	v_cvt_pk_bf16_f32 v100, v96, v97
	v_cvt_pk_bf16_f32 v96, v104, v105
	v_add_f32_e32 v104, 0, v80
	v_exp_f32_e32 v105, v84
	v_add_f32_e32 v104, v81, v104
	v_add_f32_e32 v104, v82, v104
	v_add_f32_e32 v104, v83, v104
	v_add_f32_e32 v84, v105, v104
	v_exp_f32_e32 v104, v85
	v_cvt_pk_bf16_f32 v97, v106, v107
	v_exp_f32_e32 v106, v86
	v_exp_f32_e32 v87, v87
	v_exp_f32_e32 v88, v88
	v_add_f32_e32 v84, v104, v84
	v_exp_f32_e32 v89, v89
	v_add_f32_e32 v84, v106, v84
	v_exp_f32_e32 v90, v90
	v_add_f32_e32 v84, v87, v84
	v_exp_f32_e32 v91, v91
	v_add_f32_e32 v84, v88, v84
	v_exp_f32_e32 v92, v92
	v_add_f32_e32 v84, v89, v84
	v_exp_f32_e32 v93, v93
	v_add_f32_e32 v84, v90, v84
	v_exp_f32_e32 v94, v94
	v_add_f32_e32 v84, v91, v84
	v_exp_f32_e32 v95, v95
	v_add_f32_e32 v84, v92, v84
	v_add_f32_e32 v84, v93, v84
	v_add_f32_e32 v84, v94, v84
	v_add_f32_e32 v107, v95, v84
	v_cvt_pk_bf16_f32 v84, v80, v81
	v_cvt_pk_bf16_f32 v85, v82, v83
	v_cvt_pk_bf16_f32 v80, v88, v89
	v_cvt_pk_bf16_f32 v81, v90, v91
	v_cvt_pk_bf16_f32 v82, v92, v93
	v_cvt_pk_bf16_f32 v83, v94, v95
	ds_read2_b64 v[88:91], v15 offset0:8 offset1:10
	ds_read2_b64 v[92:95], v15 offset0:12 offset1:14
	v_cvt_pk_bf16_f32 v101, v98, v99
	v_cvt_pk_bf16_f32 v102, v231, v230
	v_cvt_pk_bf16_f32 v103, v232, v103
	v_cvt_pk_bf16_f32 v86, v105, v104
	v_cvt_pk_bf16_f32 v87, v106, v87
	s_waitcnt lgkmcnt(1)
	v_mfma_f32_32x32x16_bf16 v[64:79], v[88:91], v[100:103], v[64:79]
	v_cvt_pk_bf16_f32 v98, v108, v109
	v_cvt_pk_bf16_f32 v99, v110, v111
	s_xor_b32 s3, s3, 1
	s_mul_i32 s8, s3, 0x2400
	s_lshl_b32 s3, s3, 9
	s_add_i32 s2, s2, 1
	s_sub_i32 s3, s8, s3
	v_mfma_f32_32x32x16_bf16 v[32:47], v[88:91], v[84:87], v[32:47]
	ds_read2_b64 v[88:91], v14 offset0:40 offset1:42
	v_cmp_eq_u32_e32 vcc, s2, v193
	v_add_f32_e32 v229, v229, v233
	v_add_f32_e32 v0, v0, v107
	s_or_b64 s[6:7], vcc, s[6:7]
	s_waitcnt lgkmcnt(0)
	v_mfma_f32_32x32x16_bf16 v[16:31], v[88:91], v[84:87], v[16:31]
	ds_read2_b64 v[84:87], v14 offset0:44 offset1:46
	v_add3_u32 v14, s8, v149, v227
	s_waitcnt vmcnt(3)
	ds_write_b128 v14, v[2:5]
	v_add3_u32 v2, s8, v153, v228
	s_mov_b64 s[8:9], 0x80
	s_waitcnt vmcnt(2)
	ds_write_b128 v2, v[6:9]
	v_add3_u32 v2, s3, v197, v190
	v_mfma_f32_32x32x16_bf16 v[48:63], v[88:91], v[100:103], v[48:63]
	v_lshl_add_u64 v[198:199], v[198:199], 0, s[8:9]
	s_mov_b64 s[8:9], 0x2000
	v_add_u32_e32 v3, 0x4800, v2
	v_add_u32_e32 v2, 0x5900, v2
	v_lshl_add_u64 v[200:201], v[200:201], 0, s[8:9]
	v_lshl_add_u64 v[202:203], v[202:203], 0, s[8:9]
	s_waitcnt vmcnt(1)
	ds_write2_b64 v3, v[10:11], v[12:13] offset1:1
	v_mfma_f32_32x32x16_bf16 v[64:79], v[92:95], v[96:99], v[64:79]
	s_waitcnt vmcnt(0)
	ds_write2_b64 v2, v[144:145], v[146:147] offset1:1
	s_waitcnt lgkmcnt(0)
	s_barrier
	v_mfma_f32_32x32x16_bf16 v[32:47], v[92:95], v[80:83], v[32:47]
	v_mfma_f32_32x32x16_bf16 v[48:63], v[84:87], v[96:99], v[48:63]
	v_mfma_f32_32x32x16_bf16 v[16:31], v[84:87], v[80:83], v[16:31]
	s_andn2_b64 exec, exec, s[6:7]
	s_cbranch_execz .LBB0_870
.LBB0_862:
	v_lshl_add_u64 v[14:15], v[198:199], 0, v[204:205]
	s_mov_b32 s8, 0xf240000
	v_add_co_u32_e32 v10, vcc, s8, v14
	s_mov_b32 s8, 0xf284000
	s_nop 0
	v_addc_co_u32_e32 v11, vcc, 0, v15, vcc
	v_add_co_u32_e32 v14, vcc, s8, v14
	v_lshl_add_u64 v[2:3], v[200:201], 0, v[204:205]
	v_lshl_add_u64 v[6:7], v[202:203], 0, v[204:205]
	v_addc_co_u32_e32 v15, vcc, 0, v15, vcc
	global_load_dwordx4 v[2:5], v[2:3], off
	s_and_b32 s3, s2, 1
	global_load_dwordx4 v[6:9], v[6:7], off
	s_mul_i32 s8, s3, 0x2400
	global_load_dwordx4 v[10:13], v[10:11], off offset:128
	v_add_u32_e32 v230, s8, v225
	global_load_dwordx4 v[144:147], v[14:15], off offset:128
	ds_read_b128 v[80:83], v230
	ds_read_b128 v[232:235], v230 offset:32
	s_waitcnt vmcnt(11) lgkmcnt(1)
	v_mfma_f32_32x32x16_bf16 v[96:111], v[80:83], v[132:135], v[208:223]
	s_waitcnt vmcnt(7)
	v_mfma_f32_32x32x16_bf16 v[80:95], v[80:83], v[140:143], v[160:175]
	s_waitcnt lgkmcnt(0)
	v_mfma_f32_32x32x16_bf16 v[96:111], v[232:235], v[124:127], v[96:111]
	s_waitcnt vmcnt(6)
	v_mfma_f32_32x32x16_bf16 v[80:95], v[232:235], v[136:139], v[80:95]
	ds_read_b128 v[232:235], v230 offset:64
	s_waitcnt lgkmcnt(0)
	v_mfma_f32_32x32x16_bf16 v[96:111], v[232:235], v[120:123], v[96:111]
	s_waitcnt vmcnt(5)
	v_mfma_f32_32x32x16_bf16 v[80:95], v[232:235], v[128:131], v[80:95]
	ds_read_b128 v[232:235], v230 offset:96
	s_waitcnt lgkmcnt(0)
	v_mfma_f32_32x32x16_bf16 v[96:111], v[232:235], v[112:115], v[96:111]
	s_waitcnt vmcnt(4)
	v_mfma_f32_32x32x16_bf16 v[80:95], v[232:235], v[116:119], v[80:95]
	s_nop 9
	v_max3_f32 v14, v96, v97, v98
	v_max3_f32 v15, v99, v100, v101
	v_max3_f32 v231, v102, v103, v104
	v_max3_f32 v232, v105, v106, v107
	v_max3_f32 v233, v108, v109, v110
	v_max3_f32 v14, v14, v15, v231
	v_max3_f32 v232, v232, v233, v111
	v_max_f32_e32 v14, v14, v232
	v_mov_b32_e32 v15, v14
	s_nop 1
	v_permlane32_swap_b32_e32 v14, v15
	v_max_f32_e32 v15, v15, v15
	v_max_f32_e32 v14, v14, v14
	v_max_f32_e32 v14, v14, v15
	v_sub_f32_e32 v14, v14, v208
	v_add_f32_e32 v15, 4.0, v191
	v_cmp_gt_f32_e32 vcc, v14, v15
	s_cbranch_vccz .LBB0_864
; template <int DK>
; DI void attn_item2(const u16* __restrict__ Q, int ldq, const u16* __restrict__ K, int ldk, const u16* __restrict__ Vt, int nTiles,
;                    u16* __restrict__ Gp, const u16* __restrict__ Zp, char* smem, int tid) {
;     ...
;       SOFTMAX_STEP(s0, m_run0, l_run0, o[0], pf0)
;       SOFTMAX_STEP(s1, m_run1, l_run1, o[1], pf1)
	v_max_f32_e32 v14, v14, v14
	v_max_f32_e32 v15, v191, v191
	v_max_f32_e32 v15, v15, v14
	v_sub_f32_e32 v14, v191, v15
	v_exp_f32_e32 v14, v14
	v_mov_b32_e32 v191, v15
	v_add_f32_e32 v231, v15, v208
	v_sub_f32_e32 v208, 0, v15
	v_mov_b32_e32 v209, v208
	v_mov_b32_e32 v210, v208
	v_mov_b32_e32 v211, v208
	v_mov_b32_e32 v212, v208
	v_mov_b32_e32 v213, v208
	v_mov_b32_e32 v214, v208
	v_mov_b32_e32 v215, v208
	v_mov_b32_e32 v216, v208
	v_mov_b32_e32 v217, v208
	v_mov_b32_e32 v218, v208
	v_mov_b32_e32 v219, v208
	v_mov_b32_e32 v220, v208
	v_mov_b32_e32 v221, v208
	v_mov_b32_e32 v222, v208
	v_mov_b32_e32 v223, v208
	v_sub_f32_e32 v96, v96, v231
	v_sub_f32_e32 v97, v97, v231
	v_sub_f32_e32 v98, v98, v231
	v_sub_f32_e32 v99, v99, v231
	v_sub_f32_e32 v100, v100, v231
	v_sub_f32_e32 v101, v101, v231
	v_sub_f32_e32 v102, v102, v231
	v_sub_f32_e32 v103, v103, v231
	v_sub_f32_e32 v104, v104, v231
	v_sub_f32_e32 v105, v105, v231
	v_sub_f32_e32 v106, v106, v231
	v_sub_f32_e32 v107, v107, v231
	v_sub_f32_e32 v108, v108, v231
	v_sub_f32_e32 v109, v109, v231
	v_sub_f32_e32 v110, v110, v231
	v_sub_f32_e32 v111, v111, v231
	v_pk_mul_f32 v[78:79], v[78:79], v[14:15] op_sel_hi:[1,0]
	v_pk_mul_f32 v[76:77], v[76:77], v[14:15] op_sel_hi:[1,0]
	v_pk_mul_f32 v[74:75], v[74:75], v[14:15] op_sel_hi:[1,0]
	v_pk_mul_f32 v[72:73], v[72:73], v[14:15] op_sel_hi:[1,0]
	v_pk_mul_f32 v[70:71], v[70:71], v[14:15] op_sel_hi:[1,0]
	v_pk_mul_f32 v[68:69], v[68:69], v[14:15] op_sel_hi:[1,0]
	v_pk_mul_f32 v[66:67], v[66:67], v[14:15] op_sel_hi:[1,0]
	v_pk_mul_f32 v[64:65], v[64:65], v[14:15] op_sel_hi:[1,0]
	v_pk_mul_f32 v[62:63], v[62:63], v[14:15] op_sel_hi:[1,0]
	v_pk_mul_f32 v[60:61], v[60:61], v[14:15] op_sel_hi:[1,0]
	v_pk_mul_f32 v[58:59], v[58:59], v[14:15] op_sel_hi:[1,0]
	v_pk_mul_f32 v[56:57], v[56:57], v[14:15] op_sel_hi:[1,0]
	v_pk_mul_f32 v[54:55], v[54:55], v[14:15] op_sel_hi:[1,0]
	v_pk_mul_f32 v[52:53], v[52:53], v[14:15] op_sel_hi:[1,0]
	v_pk_mul_f32 v[50:51], v[50:51], v[14:15] op_sel_hi:[1,0]
	v_pk_mul_f32 v[48:49], v[48:49], v[14:15] op_sel_hi:[1,0]
	v_mul_f32_e32 v229, v229, v14
.LBB0_864:
	v_max3_f32 v14, v80, v81, v82
	v_max3_f32 v15, v83, v84, v85
	v_max3_f32 v231, v86, v87, v88
	v_max3_f32 v232, v89, v90, v91
	v_max3_f32 v233, v92, v93, v94
	v_max3_f32 v14, v14, v15, v231
	v_max3_f32 v232, v232, v233, v95
	v_max_f32_e32 v14, v14, v232
	v_mov_b32_e32 v15, v14
	s_nop 1
	v_permlane32_swap_b32_e32 v14, v15
	v_max_f32_e32 v15, v15, v15
	v_max_f32_e32 v14, v14, v14
	v_max_f32_e32 v14, v14, v15
	v_sub_f32_e32 v14, v14, v160
	v_add_f32_e32 v15, 4.0, v189
	v_cmp_gt_f32_e32 vcc, v14, v15
	s_cbranch_vccz .LBB0_866
	v_max_f32_e32 v14, v14, v14
	v_max_f32_e32 v15, v189, v189
	v_max_f32_e32 v15, v15, v14
	v_sub_f32_e32 v14, v189, v15
	v_exp_f32_e32 v14, v14
	v_mov_b32_e32 v189, v15
	v_add_f32_e32 v231, v15, v160
	v_sub_f32_e32 v160, 0, v15
	v_mov_b32_e32 v161, v160
	v_mov_b32_e32 v162, v160
	v_mov_b32_e32 v163, v160
	v_mov_b32_e32 v164, v160
	v_mov_b32_e32 v165, v160
	v_mov_b32_e32 v166, v160
	v_mov_b32_e32 v167, v160
	v_mov_b32_e32 v168, v160
	v_mov_b32_e32 v169, v160
	v_mov_b32_e32 v170, v160
	v_mov_b32_e32 v171, v160
	v_mov_b32_e32 v172, v160
	v_mov_b32_e32 v173, v160
	v_mov_b32_e32 v174, v160
	v_mov_b32_e32 v175, v160
	v_sub_f32_e32 v80, v80, v231
	v_sub_f32_e32 v81, v81, v231
	v_sub_f32_e32 v82, v82, v231
	v_sub_f32_e32 v83, v83, v231
	v_sub_f32_e32 v84, v84, v231
	v_sub_f32_e32 v85, v85, v231
	v_sub_f32_e32 v86, v86, v231
	v_sub_f32_e32 v87, v87, v231
	v_sub_f32_e32 v88, v88, v231
	v_sub_f32_e32 v89, v89, v231
	v_sub_f32_e32 v90, v90, v231
	v_sub_f32_e32 v91, v91, v231
	v_sub_f32_e32 v92, v92, v231
	v_sub_f32_e32 v93, v93, v231
	v_sub_f32_e32 v94, v94, v231
	v_sub_f32_e32 v95, v95, v231
	v_pk_mul_f32 v[46:47], v[46:47], v[14:15] op_sel_hi:[1,0]
	v_pk_mul_f32 v[44:45], v[44:45], v[14:15] op_sel_hi:[1,0]
	v_pk_mul_f32 v[42:43], v[42:43], v[14:15] op_sel_hi:[1,0]
	v_pk_mul_f32 v[40:41], v[40:41], v[14:15] op_sel_hi:[1,0]
	v_pk_mul_f32 v[38:39], v[38:39], v[14:15] op_sel_hi:[1,0]
	v_pk_mul_f32 v[36:37], v[36:37], v[14:15] op_sel_hi:[1,0]
	v_pk_mul_f32 v[34:35], v[34:35], v[14:15] op_sel_hi:[1,0]
	v_pk_mul_f32 v[32:33], v[32:33], v[14:15] op_sel_hi:[1,0]
	v_pk_mul_f32 v[30:31], v[30:31], v[14:15] op_sel_hi:[1,0]
	v_pk_mul_f32 v[28:29], v[28:29], v[14:15] op_sel_hi:[1,0]
	v_pk_mul_f32 v[26:27], v[26:27], v[14:15] op_sel_hi:[1,0]
	v_pk_mul_f32 v[24:25], v[24:25], v[14:15] op_sel_hi:[1,0]
	v_pk_mul_f32 v[22:23], v[22:23], v[14:15] op_sel_hi:[1,0]
	v_pk_mul_f32 v[20:21], v[20:21], v[14:15] op_sel_hi:[1,0]
	v_pk_mul_f32 v[18:19], v[18:19], v[14:15] op_sel_hi:[1,0]
	v_pk_mul_f32 v[16:17], v[16:17], v[14:15] op_sel_hi:[1,0]
	v_mul_f32_e32 v0, v0, v14
; #define MFMA(a, b, c) __builtin_amdgcn_mfma_f32_32x32x16_bf16((a), (b), (c), 0, 0, 0)
; template <int DK>
; DI void attn_item2(const u16* __restrict__ Q, int ldq, const u16* __restrict__ K, int ldk, const u16* __restrict__ Vt, int nTiles,
;                    u16* __restrict__ Gp, const u16* __restrict__ Zp, char* smem, int tid) {
;     ...
;     for (int kb = 0; kb < 2; kb++) {
;       f32x16 s0, s1;
; #pragma unroll
;       for (int i = 0; i < 16; i++) { s0[i] = 0.f; s1[i] = 0.f; }
; #pragma unroll
;       for (int ks = 0; ks < KS; ks++) {
;         bf16x8 a = *(const bf16x8*)&Ks[buf][kb * 32 + r][ks * 16 + h * 8];
;         s0 = MFMA(a, qf[0][ks], s0);
;         s1 = MFMA(a, qf[1][ks], s1);
;       }
;       bf16x8 pf0[2], pf1[2];
;     ...
;       SOFTMAX_STEP(s0, m_run0, l_run0, o[0], pf0)
;       SOFTMAX_STEP(s1, m_run1, l_run1, o[1], pf1)
;     ...
; #pragma unroll
;       for (int db = 0; db < 2; db++)
; #pragma unroll
;         for (int sx = 0; sx < 2; sx++) {
;           const u16* vp = &Vs[buf][db * 32 + r][32 * kb + 16 * sx + 4 * h];
;           uint2 lo = *(const uint2*)vp, hi = *(const uint2*)(vp + 8);
;           uint4 u; u.x = lo.x; u.y = lo.y; u.z = hi.x; u.w = hi.y;
;           const bf16x8 a = __builtin_bit_cast(bf16x8, u);
;           o[0][db] = MFMA(a, pf0[sx], o[0][db]);
;           o[1][db] = MFMA(a, pf1[sx], o[1][db]);
;         }
.LBB0_866:
	v_exp_f32_e32 v14, v96
	v_exp_f32_e32 v96, v97
	v_exp_f32_e32 v97, v98
	v_exp_f32_e32 v98, v99
	v_add_f32_e32 v15, 0, v14
	v_exp_f32_e32 v99, v100
	v_add_f32_e32 v15, v96, v15
	v_exp_f32_e32 v231, v101
	v_add_f32_e32 v15, v97, v15
	v_exp_f32_e32 v232, v102
	v_add_f32_e32 v15, v98, v15
	v_exp_f32_e32 v103, v103
	v_add_f32_e32 v15, v99, v15
	v_exp_f32_e32 v104, v104
	v_add_f32_e32 v15, v231, v15
	v_exp_f32_e32 v105, v105
	v_add_f32_e32 v15, v232, v15
	v_exp_f32_e32 v106, v106
	v_add_f32_e32 v15, v103, v15
	v_exp_f32_e32 v107, v107
	v_add_f32_e32 v15, v104, v15
	v_exp_f32_e32 v108, v108
	v_add_f32_e32 v15, v105, v15
	v_exp_f32_e32 v109, v109
	v_add_f32_e32 v15, v106, v15
	v_exp_f32_e32 v110, v110
	v_add_f32_e32 v15, v107, v15
	v_exp_f32_e32 v111, v111
	v_add_f32_e32 v15, v108, v15
	v_add_f32_e32 v15, v109, v15
	v_add_f32_e32 v15, v110, v15
	v_add_f32_e32 v15, v111, v15
	v_add_f32_e32 v229, v229, v15
	v_cvt_pk_bf16_f32 v102, v99, v231
	v_exp_f32_e32 v231, v80
	v_cvt_pk_bf16_f32 v103, v232, v103
	v_exp_f32_e32 v232, v81
	v_exp_f32_e32 v233, v82
	v_exp_f32_e32 v234, v83
	v_exp_f32_e32 v235, v84
	v_exp_f32_e32 v236, v85
	v_exp_f32_e32 v237, v86
	v_exp_f32_e32 v238, v87
	v_exp_f32_e32 v239, v88
	v_exp_f32_e32 v240, v89
	v_exp_f32_e32 v241, v90
	v_exp_f32_e32 v242, v91
	v_exp_f32_e32 v243, v92
	s_mul_i32 s8, s3, 0x2200
	v_exp_f32_e32 v244, v93
	v_cvt_pk_bf16_f32 v100, v14, v96
	v_add_u32_e32 v14, s8, v226
	v_exp_f32_e32 v245, v94
	v_exp_f32_e32 v246, v95
	v_add_u32_e32 v15, 0x4800, v14
	ds_read2_b64 v[88:91], v15 offset1:2
	ds_read2_b64 v[92:95], v15 offset0:4 offset1:6
	v_cvt_pk_bf16_f32 v101, v97, v98
	v_cvt_pk_bf16_f32 v84, v231, v232
	v_cvt_pk_bf16_f32 v85, v233, v234
	v_cvt_pk_bf16_f32 v86, v235, v236
	v_cvt_pk_bf16_f32 v87, v237, v238
	v_add_u32_e32 v14, 0x5800, v14
	s_waitcnt lgkmcnt(1)
	v_mfma_f32_32x32x16_bf16 v[64:79], v[88:91], v[100:103], v[64:79]
	v_cvt_pk_bf16_f32 v80, v239, v240
	v_cvt_pk_bf16_f32 v81, v241, v242
	v_cvt_pk_bf16_f32 v82, v243, v244
	v_cvt_pk_bf16_f32 v83, v245, v246
	v_cvt_pk_bf16_f32 v96, v104, v105
	v_cvt_pk_bf16_f32 v97, v106, v107
	v_cvt_pk_bf16_f32 v98, v108, v109
	v_mfma_f32_32x32x16_bf16 v[32:47], v[88:91], v[84:87], v[32:47]
	ds_read2_b64 v[88:91], v14 offset0:32 offset1:34
	v_cvt_pk_bf16_f32 v99, v110, v111
	s_waitcnt lgkmcnt(0)
	v_mfma_f32_32x32x16_bf16 v[16:31], v[88:91], v[84:87], v[16:31]
	ds_read2_b64 v[84:87], v14 offset0:36 offset1:38
	v_mfma_f32_32x32x16_bf16 v[48:63], v[88:91], v[100:103], v[48:63]
	v_mfma_f32_32x32x16_bf16 v[32:47], v[92:95], v[80:83], v[32:47]
	s_waitcnt lgkmcnt(0)
	v_mfma_f32_32x32x16_bf16 v[16:31], v[84:87], v[80:83], v[16:31]
	ds_read_b128 v[80:83], v230 offset:4608
	ds_read_b128 v[248:251], v230 offset:4640
	v_mfma_f32_32x32x16_bf16 v[64:79], v[92:95], v[96:99], v[64:79]
	v_mfma_f32_32x32x16_bf16 v[48:63], v[84:87], v[96:99], v[48:63]
	s_waitcnt lgkmcnt(1)
	v_mfma_f32_32x32x16_bf16 v[96:111], v[80:83], v[132:135], v[208:223]
	v_mfma_f32_32x32x16_bf16 v[80:95], v[80:83], v[140:143], v[160:175]
	s_waitcnt lgkmcnt(0)
	v_mfma_f32_32x32x16_bf16 v[96:111], v[248:251], v[124:127], v[96:111]
	v_mfma_f32_32x32x16_bf16 v[80:95], v[248:251], v[136:139], v[80:95]
	ds_read_b128 v[248:251], v230 offset:4672
	s_waitcnt lgkmcnt(0)
	v_mfma_f32_32x32x16_bf16 v[96:111], v[248:251], v[120:123], v[96:111]
	v_mfma_f32_32x32x16_bf16 v[80:95], v[248:251], v[128:131], v[80:95]
	ds_read_b128 v[248:251], v230 offset:4704
	s_waitcnt lgkmcnt(0)
	v_mfma_f32_32x32x16_bf16 v[96:111], v[248:251], v[112:115], v[96:111]
	v_mfma_f32_32x32x16_bf16 v[80:95], v[248:251], v[116:119], v[80:95]
	s_nop 10
	v_max3_f32 v230, v96, v97, v98
	v_max3_f32 v247, v99, v100, v101
	v_max3_f32 v248, v102, v103, v104
	v_max3_f32 v249, v105, v106, v107
	v_max3_f32 v250, v108, v109, v110
	v_max3_f32 v230, v230, v247, v248
	v_max3_f32 v249, v249, v250, v111
	v_max_f32_e32 v230, v230, v249
	v_mov_b32_e32 v247, v230
	s_nop 1
	v_permlane32_swap_b32_e32 v230, v247
	v_max_f32_e32 v247, v247, v247
	v_max_f32_e32 v230, v230, v230
	v_max_f32_e32 v230, v230, v247
	v_sub_f32_e32 v230, v230, v208
	v_add_f32_e32 v247, 4.0, v191
	v_cmp_gt_f32_e32 vcc, v230, v247
	s_cbranch_vccz .LBB0_868
	v_max_f32_e32 v230, v230, v230
	v_max_f32_e32 v247, v191, v191
	v_max_f32_e32 v247, v247, v230
	v_sub_f32_e32 v191, v191, v247
	v_exp_f32_e32 v230, v191
	v_mov_b32_e32 v191, v247
	v_add_f32_e32 v248, v247, v208
	v_sub_f32_e32 v208, 0, v247
	v_mov_b32_e32 v209, v208
	v_mov_b32_e32 v210, v208
	v_mov_b32_e32 v211, v208
	v_mov_b32_e32 v212, v208
	v_mov_b32_e32 v213, v208
	v_mov_b32_e32 v214, v208
	v_mov_b32_e32 v215, v208
	v_mov_b32_e32 v216, v208
	v_mov_b32_e32 v217, v208
	v_mov_b32_e32 v218, v208
	v_mov_b32_e32 v219, v208
	v_mov_b32_e32 v220, v208
	v_mov_b32_e32 v221, v208
	v_mov_b32_e32 v222, v208
	v_mov_b32_e32 v223, v208
	v_sub_f32_e32 v96, v96, v248
	v_sub_f32_e32 v97, v97, v248
	v_sub_f32_e32 v98, v98, v248
	v_sub_f32_e32 v99, v99, v248
	v_sub_f32_e32 v100, v100, v248
	v_sub_f32_e32 v101, v101, v248
	v_sub_f32_e32 v102, v102, v248
	v_sub_f32_e32 v103, v103, v248
	v_sub_f32_e32 v104, v104, v248
	v_sub_f32_e32 v105, v105, v248
	v_sub_f32_e32 v106, v106, v248
	v_sub_f32_e32 v107, v107, v248
	v_sub_f32_e32 v108, v108, v248
	v_sub_f32_e32 v109, v109, v248
	v_sub_f32_e32 v110, v110, v248
	v_sub_f32_e32 v111, v111, v248
	v_pk_mul_f32 v[78:79], v[78:79], v[230:231] op_sel_hi:[1,0]
	v_pk_mul_f32 v[76:77], v[76:77], v[230:231] op_sel_hi:[1,0]
	v_pk_mul_f32 v[74:75], v[74:75], v[230:231] op_sel_hi:[1,0]
	v_pk_mul_f32 v[72:73], v[72:73], v[230:231] op_sel_hi:[1,0]
	v_pk_mul_f32 v[70:71], v[70:71], v[230:231] op_sel_hi:[1,0]
	v_pk_mul_f32 v[68:69], v[68:69], v[230:231] op_sel_hi:[1,0]
	v_pk_mul_f32 v[66:67], v[66:67], v[230:231] op_sel_hi:[1,0]
	v_pk_mul_f32 v[64:65], v[64:65], v[230:231] op_sel_hi:[1,0]
	v_pk_mul_f32 v[62:63], v[62:63], v[230:231] op_sel_hi:[1,0]
	v_pk_mul_f32 v[60:61], v[60:61], v[230:231] op_sel_hi:[1,0]
	v_pk_mul_f32 v[58:59], v[58:59], v[230:231] op_sel_hi:[1,0]
	v_pk_mul_f32 v[56:57], v[56:57], v[230:231] op_sel_hi:[1,0]
	v_pk_mul_f32 v[54:55], v[54:55], v[230:231] op_sel_hi:[1,0]
	v_pk_mul_f32 v[52:53], v[52:53], v[230:231] op_sel_hi:[1,0]
	v_pk_mul_f32 v[50:51], v[50:51], v[230:231] op_sel_hi:[1,0]
	v_pk_mul_f32 v[48:49], v[48:49], v[230:231] op_sel_hi:[1,0]
	v_mul_f32_e32 v229, v229, v230
; #define MFMA(a, b, c) __builtin_amdgcn_mfma_f32_32x32x16_bf16((a), (b), (c), 0, 0, 0)
; #define GLOAD(t) { const int pos0_ = TILE_POS(t); \
;     rk0 = *(const uint4*)(K + (size_t)(pos0_ + kr0) * ldk + kc0); rk1 = *(const uint4*)(K + (size_t)(pos0_ + kr1) * ldk + kc1); \
;     if (NKC == 3) rk2 = *(const uint4*)(K + (size_t)(pos0_ + kr2) * ldk + kc2); \
;     rv0 = *(const uint4*)(Vt + (size_t)vd0 * SEQA + pos0_ + vk0); rv1 = *(const uint4*)(Vt + (size_t)(vd0 + 32) * SEQA + pos0_ + vk0); }
; #define GLOAD(t) { const int pos0_ = (t) * 64; \
;     rk0 = *(const uint4*)(K + (size_t)(pos0_ + kr0) * ldk + kc0); rk1 = *(const uint4*)(K + (size_t)(pos0_ + kr1) * ldk + kc1); \
;     if (NKC == 3) rk2 = *(const uint4*)(K + (size_t)(pos0_ + kr2) * ldk + kc2); \
;     rv0 = *(const uint4*)(Vt + (size_t)vd0 * SEQA + pos0_ + vk0); rv1 = *(const uint4*)(Vt + (size_t)(vd0 + 32) * SEQA + pos0_ + vk0); }
; template <int DK>
; DI void attn_item2(const u16* __restrict__ Q, int ldq, const u16* __restrict__ K, int ldk, const u16* __restrict__ Vt, int nTiles,
;                    u16* __restrict__ Gp, const u16* __restrict__ Zp, char* smem, int tid) {
;     ...
;   for (int t = 0; t < nTiles; t++) {
;     const int buf = t & 1;
;     if (t + 1 < nTiles) GLOAD(t + 1);
; #pragma unroll
;     for (int kb = 0; kb < 2; kb++) {
;       f32x16 s0, s1;
; #pragma unroll
;       for (int i = 0; i < 16; i++) { s0[i] = 0.f; s1[i] = 0.f; }
; #pragma unroll
;       for (int ks = 0; ks < KS; ks++) {
;         bf16x8 a = *(const bf16x8*)&Ks[buf][kb * 32 + r][ks * 16 + h * 8];
;         s0 = MFMA(a, qf[0][ks], s0);
;         s1 = MFMA(a, qf[1][ks], s1);
;       }
.LBB0_868:
	v_add_f32_e32 v230, 0, v231
	v_add_f32_e32 v230, v232, v230
	v_add_f32_e32 v230, v233, v230
	v_add_f32_e32 v230, v234, v230
	v_add_f32_e32 v230, v235, v230
	v_add_f32_e32 v230, v236, v230
	v_add_f32_e32 v230, v237, v230
	v_add_f32_e32 v230, v238, v230
	v_add_f32_e32 v230, v239, v230
	v_add_f32_e32 v230, v240, v230
	v_add_f32_e32 v230, v241, v230
	v_add_f32_e32 v230, v242, v230
	v_add_f32_e32 v230, v243, v230
	v_add_f32_e32 v230, v244, v230
	v_add_f32_e32 v230, v245, v230
	v_add_f32_e32 v230, v246, v230
	v_add_f32_e32 v0, v0, v230
	v_max3_f32 v230, v80, v81, v82
	v_max3_f32 v231, v83, v84, v85
	v_max3_f32 v232, v86, v87, v88
	v_max3_f32 v233, v89, v90, v91
	v_max3_f32 v234, v92, v93, v94
	v_max3_f32 v230, v230, v231, v232
	v_max3_f32 v233, v233, v234, v95
	v_max_f32_e32 v230, v230, v233
	v_mov_b32_e32 v231, v230
	s_nop 1
	v_permlane32_swap_b32_e32 v230, v231
	v_max_f32_e32 v231, v231, v231
	v_max_f32_e32 v230, v230, v230
	v_max_f32_e32 v230, v230, v231
	v_sub_f32_e32 v230, v230, v160
	v_add_f32_e32 v231, 4.0, v189
	v_cmp_gt_f32_e32 vcc, v230, v231
	s_cbranch_vccz .LBB0_861
	v_max_f32_e32 v230, v230, v230
	v_max_f32_e32 v231, v189, v189
	v_max_f32_e32 v231, v231, v230
	v_sub_f32_e32 v189, v189, v231
	v_exp_f32_e32 v230, v189
	v_mov_b32_e32 v189, v231
	v_add_f32_e32 v232, v231, v160
	v_sub_f32_e32 v160, 0, v231
	v_mov_b32_e32 v161, v160
	v_mov_b32_e32 v162, v160
	v_mov_b32_e32 v163, v160
	v_mov_b32_e32 v164, v160
	v_mov_b32_e32 v165, v160
	v_mov_b32_e32 v166, v160
	v_mov_b32_e32 v167, v160
	v_mov_b32_e32 v168, v160
	v_mov_b32_e32 v169, v160
	v_mov_b32_e32 v170, v160
	v_mov_b32_e32 v171, v160
	v_mov_b32_e32 v172, v160
	v_mov_b32_e32 v173, v160
	v_mov_b32_e32 v174, v160
	v_mov_b32_e32 v175, v160
	v_sub_f32_e32 v80, v80, v232
	v_sub_f32_e32 v81, v81, v232
	v_sub_f32_e32 v82, v82, v232
	v_sub_f32_e32 v83, v83, v232
	v_sub_f32_e32 v84, v84, v232
	v_sub_f32_e32 v85, v85, v232
	v_sub_f32_e32 v86, v86, v232
	v_sub_f32_e32 v87, v87, v232
	v_sub_f32_e32 v88, v88, v232
	v_sub_f32_e32 v89, v89, v232
	v_sub_f32_e32 v90, v90, v232
	v_sub_f32_e32 v91, v91, v232
	v_sub_f32_e32 v92, v92, v232
	v_sub_f32_e32 v93, v93, v232
	v_sub_f32_e32 v94, v94, v232
	v_sub_f32_e32 v95, v95, v232
	v_pk_mul_f32 v[46:47], v[46:47], v[230:231] op_sel_hi:[1,0]
	v_pk_mul_f32 v[44:45], v[44:45], v[230:231] op_sel_hi:[1,0]
	v_pk_mul_f32 v[42:43], v[42:43], v[230:231] op_sel_hi:[1,0]
	v_pk_mul_f32 v[40:41], v[40:41], v[230:231] op_sel_hi:[1,0]
	v_pk_mul_f32 v[38:39], v[38:39], v[230:231] op_sel_hi:[1,0]
	v_pk_mul_f32 v[36:37], v[36:37], v[230:231] op_sel_hi:[1,0]
	v_pk_mul_f32 v[34:35], v[34:35], v[230:231] op_sel_hi:[1,0]
	v_pk_mul_f32 v[32:33], v[32:33], v[230:231] op_sel_hi:[1,0]
	v_pk_mul_f32 v[30:31], v[30:31], v[230:231] op_sel_hi:[1,0]
	v_pk_mul_f32 v[28:29], v[28:29], v[230:231] op_sel_hi:[1,0]
	v_pk_mul_f32 v[26:27], v[26:27], v[230:231] op_sel_hi:[1,0]
	v_pk_mul_f32 v[24:25], v[24:25], v[230:231] op_sel_hi:[1,0]
	v_pk_mul_f32 v[22:23], v[22:23], v[230:231] op_sel_hi:[1,0]
	v_pk_mul_f32 v[20:21], v[20:21], v[230:231] op_sel_hi:[1,0]
	v_pk_mul_f32 v[18:19], v[18:19], v[230:231] op_sel_hi:[1,0]
	v_pk_mul_f32 v[16:17], v[16:17], v[230:231] op_sel_hi:[1,0]
	v_mul_f32_e32 v0, v0, v230
	s_branch .LBB0_861
.LBB0_870:
	s_or_b64 exec, exec, s[6:7]
	v_lshlrev_b32_e32 v14, 2, v206
	v_add_u32_e32 v14, 0xd000, v14
	ds_read_b32 v160, v14 offset:0
	ds_read_b32 v161, v14 offset:1024
	ds_read_b32 v162, v14 offset:2048
	ds_read_b32 v163, v14 offset:3072
	ds_read_b32 v164, v14 offset:4096
	ds_read_b32 v165, v14 offset:5120
	ds_read_b32 v166, v14 offset:6144
	ds_read_b32 v167, v14 offset:7168
	ds_read_b32 v168, v14 offset:8192
	ds_read_b32 v169, v14 offset:9216
	ds_read_b32 v170, v14 offset:10240
	ds_read_b32 v171, v14 offset:11264
	ds_read_b32 v172, v14 offset:12288
	ds_read_b32 v173, v14 offset:13312
	ds_read_b32 v174, v14 offset:14336
	ds_read_b32 v175, v14 offset:15360
	s_waitcnt lgkmcnt(0)
	v_and_b32_e32 v10, 1, v193
	v_mad_u32_u24 v14, v10, s28, v225
	ds_read_b128 v[2:5], v14
	ds_read_b128 v[6:9], v14 offset:32
	s_waitcnt lgkmcnt(1)
	v_mfma_f32_32x32x16_bf16 v[96:111], v[2:5], v[132:135], 0
	v_mfma_f32_32x32x16_bf16 v[80:95], v[2:5], v[140:143], 0
	ds_read_b128 v[2:5], v14 offset:64
	s_waitcnt lgkmcnt(1)
	v_mfma_f32_32x32x16_bf16 v[96:111], v[6:9], v[124:127], v[96:111]
	v_mfma_f32_32x32x16_bf16 v[80:95], v[6:9], v[136:139], v[80:95]
	s_waitcnt lgkmcnt(0)
	v_mfma_f32_32x32x16_bf16 v[96:111], v[2:5], v[120:123], v[96:111]
	v_mfma_f32_32x32x16_bf16 v[80:95], v[2:5], v[128:131], v[80:95]
	ds_read_b128 v[2:5], v14 offset:96
	s_waitcnt lgkmcnt(0)
	v_mfma_f32_32x32x16_bf16 v[96:111], v[2:5], v[112:115], v[96:111]
	v_mfma_f32_32x32x16_bf16 v[80:95], v[2:5], v[116:119], v[80:95]
	s_nop 10
	v_max3_f32 v2, v96, v97, v98
	v_max3_f32 v3, v99, v100, v101
	v_max3_f32 v4, v102, v103, v104
	v_max3_f32 v5, v105, v106, v107
	v_max3_f32 v6, v108, v109, v110
	v_max3_f32 v2, v2, v3, v4
	v_max3_f32 v5, v5, v6, v111
	v_max_f32_e32 v2, v2, v5
	v_mov_b32_e32 v3, v2
	s_nop 1
	v_permlane32_swap_b32_e32 v2, v3
	v_max_f32_e32 v3, v3, v3
	v_max_f32_e32 v2, v2, v2
	v_max_f32_e32 v2, v2, v3
	v_add_f32_e32 v3, 4.0, v191
	v_cmp_gt_f32_e32 vcc, v2, v3
	s_cbranch_vccz .LBB0_872
	v_max_f32_e32 v2, v2, v2
	v_max_f32_e32 v3, v191, v191
	v_max_f32_e32 v3, v3, v2
	v_sub_f32_e32 v2, v191, v3
	v_exp_f32_e32 v2, v2
	v_mov_b32_e32 v191, v3
	v_pk_mul_f32 v[78:79], v[78:79], v[2:3] op_sel_hi:[1,0]
	v_pk_mul_f32 v[76:77], v[76:77], v[2:3] op_sel_hi:[1,0]
	v_pk_mul_f32 v[74:75], v[74:75], v[2:3] op_sel_hi:[1,0]
	v_pk_mul_f32 v[72:73], v[72:73], v[2:3] op_sel_hi:[1,0]
	v_pk_mul_f32 v[70:71], v[70:71], v[2:3] op_sel_hi:[1,0]
	v_pk_mul_f32 v[68:69], v[68:69], v[2:3] op_sel_hi:[1,0]
	v_pk_mul_f32 v[66:67], v[66:67], v[2:3] op_sel_hi:[1,0]
	v_pk_mul_f32 v[64:65], v[64:65], v[2:3] op_sel_hi:[1,0]
	v_pk_mul_f32 v[62:63], v[62:63], v[2:3] op_sel_hi:[1,0]
	v_pk_mul_f32 v[60:61], v[60:61], v[2:3] op_sel_hi:[1,0]
	v_pk_mul_f32 v[58:59], v[58:59], v[2:3] op_sel_hi:[1,0]
	v_pk_mul_f32 v[56:57], v[56:57], v[2:3] op_sel_hi:[1,0]
	v_pk_mul_f32 v[54:55], v[54:55], v[2:3] op_sel_hi:[1,0]
	v_pk_mul_f32 v[52:53], v[52:53], v[2:3] op_sel_hi:[1,0]
	v_pk_mul_f32 v[50:51], v[50:51], v[2:3] op_sel_hi:[1,0]
	v_pk_mul_f32 v[48:49], v[48:49], v[2:3] op_sel_hi:[1,0]
	v_mul_f32_e32 v229, v229, v2

; #define DECODE2(it) int b, hd; size_t q0; int nT; \
;     if ((it) < NL2) { b = (it) >> 6; hd = ((it) >> 4) & 3; q0 = (size_t)b * SEQA + CTXL + ((it) & 15) * 256; nT = 68; } \
;     else { int j_ = (it) - NL2; b = j_ >> 2; hd = j_ & 3; q0 = (size_t)b * SEQA; nT = 4; }
; DI int fetch_item(unsigned* ctr, char* smem) {
;   volatile int* slot = (volatile int*)(smem + SMEM_BYTES - 16);
;   __syncthreads();
;   if (threadIdx.x == 0) *slot = (int)__hip_atomic_fetch_add(ctr, 1u, __ATOMIC_RELAXED, __HIP_MEMORY_SCOPE_AGENT);
;   __syncthreads();
;   return *slot;
; }
; DI void phase_mix(const Params& p, int l, char* smem, int tid) {
;     ...
;   for (int it = fetch_item(q, smem); it < NT2; it = fetch_item(q, smem)) {
;     DECODE2(it)
;     const int hk = hd >> 1;
;     attn_item2<64>(p.QD + q0 * 256 + hd * 64, 256, p.KD + ((size_t)b * 2 + hk) * SEQA * 64, 64, p.VtAD + ((size_t)b * 384 + 256 + hk * 64) * SEQA, nT,
;                    p.G + q0 * 1024 + 768 + hd * 64, p.Pk + q0 * PKW + 768 + 768 + hd * 64, smem, tid);
;   }
.LBB0_881:
	s_or_b64 exec, exec, s[0:1]
	v_lshlrev_b32_e32 v14, 2, v206
	ds_read_b32 v208, v14 offset:36864
	ds_read_b32 v209, v14 offset:37888
	ds_read_b32 v210, v14 offset:38912
	ds_read_b32 v211, v14 offset:39936
	ds_read_b32 v212, v14 offset:40960
	ds_read_b32 v213, v14 offset:41984
	ds_read_b32 v214, v14 offset:43008
	ds_read_b32 v215, v14 offset:44032
	ds_read_b32 v216, v14 offset:45056
	ds_read_b32 v217, v14 offset:46080
	ds_read_b32 v218, v14 offset:47104
	ds_read_b32 v219, v14 offset:48128
	ds_read_b32 v220, v14 offset:49152
	ds_read_b32 v221, v14 offset:50176
	ds_read_b32 v222, v14 offset:51200
	ds_read_b32 v223, v14 offset:52224
	s_waitcnt lgkmcnt(0)
	s_barrier
	s_and_saveexec_b64 s[0:1], s[92:93]
	s_movk_i32 s11, 0x400
	s_movk_i32 s8, 0xd0
	s_mov_b32 s16, 0xf149f2ca
	s_cbranch_execz .LBB0_885
	s_mov_b64 s[4:5], exec
	v_mbcnt_lo_u32_b32 v0, s4, 0
	v_mbcnt_hi_u32_b32 v0, s5, v0
	v_cmp_eq_u32_e32 vcc, 0, v0
	s_and_saveexec_b64 s[2:3], vcc
	s_cbranch_execz .LBB0_884
	s_bcnt1_i32_b64 s4, s[4:5]
	v_mov_b32_e32 v2, s4
	v_readlane_b32 s4, v254, 51
	v_readlane_b32 s5, v254, 52
	s_nop 4
	global_atomic_add v2, v1, v2, s[4:5] offset:256 sc0
